# mem-kv GEMM tiles (64, blocks 0..63) moved from a 15th inproj round to after the inproj grid barrier; mLSTM-A items rebalanced (blocks 0..63 take 10, others 18)
# speedup vs baseline: 1.0065x; 1.0065x over previous
; DI bool tile_of(int it, int MT, int NT, int& mt, int& nt) {
;   const int nb = gridDim.x;
;   if ((nb & 7) == 0 && (MT & 7) == 0) {
;     const int x = blockIdx.x & 7, slot = blockIdx.x >> 3, nx = nb >> 3, j = slot + it * nx, per = (MT >> 3) * NT;
;     if (j >= per) return false;
;     if (NT == 14 && (MT >> 3) == 32) {
;       const int r = j / 28, w = j - r * 28, nh = r >> 3, mg = r & 7;
;       mt = x * 32 + mg * 4 + w / 7; nt = nh * 7 + w % 7; return true;
;     }
;     mt = x * (MT >> 3) + j / NT; nt = j % NT; return true;
;   }
;   const int j = blockIdx.x + it * nb;
;   if (j >= MT * NT) return false;
;   mt = j / NT; nt = j % NT; return true;
; DI void phase_inproj(const Params& p, char* lds) {
;     ...
;   for (int it = 0;; ++it) {
;     if (!tile_of(it, 8, 8, mt, nt)) break;
.LBB0_240:
	s_and_b64 vcc, exec, s[28:29]
	s_cbranch_vccz .LBB0_245
	s_mul_i32 s20, s12, s70
	s_add_i32 s20, s20, s94
	s_mov_b64 s[18:19], 0
	s_cmp_gt_i32 s20, -1
	s_mov_b64 s[16:17], 0
	s_mov_b32 s93, s55
	s_mov_b32 s92, s54
	s_cbranch_scc1 .LBB0_243
	s_ashr_i32 s16, s20, 31
	s_lshr_b32 s16, s16, 29
	s_add_i32 s16, s20, s16
	s_ashr_i32 s92, s16, 3
	s_and_b32 s16, s16, -8
	s_sub_i32 s93, s20, s16
	s_mov_b64 s[16:17], -1

; DI bool tile_of(int it, int MT, int NT, int& mt, int& nt) {
;   const int nb = gridDim.x;
;   if ((nb & 7) == 0 && (MT & 7) == 0) {
;     const int x = blockIdx.x & 7, slot = blockIdx.x >> 3, nx = nb >> 3, j = slot + it * nx, per = (MT >> 3) * NT;
;     if (j >= per) return false;
;     if (NT == 14 && (MT >> 3) == 32) {
;       const int r = j / 28, w = j - r * 28, nh = r >> 3, mg = r & 7;
;       mt = x * 32 + mg * 4 + w / 7; nt = nh * 7 + w % 7; return true;
;     }
;     mt = x * (MT >> 3) + j / NT; nt = j % NT; return true;
; DI void phase_inproj(const Params& p, char* lds) {
;     ...
;   for (int it = 0;; ++it) {
;     if (!tile_of(it, 8, 8, mt, nt)) break;
.LBB0_245:
.LBB0_246:
	v_readlane_b32 s16, v250, 11
	s_mul_i32 s18, s12, s16
	v_readlane_b32 s16, v250, 10
	s_add_i32 s18, s18, s16
	s_cmp_gt_i32 s18, -1
	s_mov_b64 s[16:17], 0
	s_cbranch_scc1 .LBB0_248
	s_ashr_i32 s16, s18, 31
	s_lshr_b32 s16, s16, 29
	s_add_i32 s16, s18, s16
	s_ashr_i32 s17, s16, 3
	v_readlane_b32 s19, v250, 12
	s_and_b32 s16, s16, -8
	s_add_i32 s54, s17, s19
	s_sub_i32 s55, s18, s16
	s_mov_b64 s[16:17], -1

; DI void phase_inproj(const Params& p, char* lds) {
;     ...
;   for (int it = 0;; ++it) {
;     if (!tile_of(it, 8, 8, mt, nt)) break;
;     const int m0 = mt * 256, n0 = nt * 256;
;     const u16* Am = (const u16*)(ws + OFF_MEMB) + (size_t)m0 * 1024; const u16* Bm = (const u16*)(ws + OFF_WKV) + (size_t)n0 * 1024;
;     f32x4 acc[2][2][4][2];
;     if (n0 >= 1024) { gemm8p<0>(Am, Bm, acc, lds); epilogue8<0, 0>(acc, lds, (u16*)(ws + OFF_VTX) + ((size_t)((m0 >> 8) * 1024 + (n0 - 1024))) * 256, 256, nullptr); }
;     else { gemm8p<1>(Am, Bm, acc, lds); epilogue8<1, 0>(acc, lds, (u16*)(ws + OFF_KX) + (size_t)m0 * 1024 + n0, 1024, nullptr); }
;   }
; DI void phase_mixA(const Params& p, char* lds) {
;   for (int it = blockIdx.x; it < 4096; it += gridDim.x) mlstmA_item(p, lds, it);
.LBB0_321:
	s_or_b64 exec, exec, s[0:1]
	s_cmpk_gt_i32 s94, 0xfff
	s_waitcnt lgkmcnt(0)
	s_barrier
.Lkvm_237:
	s_add_u32 s14, s68, 0x1700000
	s_addc_u32 s15, s69, 0
	s_and_b32 s0, s94, 7
	v_writelane_b32 v250, s0, 12
	s_add_u32 s0, s68, 0x1b00000
	v_writelane_b32 v250, s0, 13
	s_addc_u32 s0, s69, 0
	s_add_u32 s53, s68, 0x1f00000
	v_writelane_b32 v250, s0, 14
	s_addc_u32 s2, s69, 0
	s_mov_b32 s12, 0
	s_add_i32 s33, 0, 0x10000
	s_mov_b64 s[0:1], 0x20000
	s_add_i32 s3, 0, 0x14000
	s_mov_b64 s[4:5], 0x40000
	s_mov_b64 s[6:7], 0x60000
	s_add_i32 s90, 0, 0x18000
	s_mov_b64 s[8:9], 0x80
	s_mov_b64 s[10:11], 0x20080
	s_add_i32 s91, 0, 0x1c000
	s_mov_b64 s[26:27], 0x1740080
	s_mov_b64 s[42:43], 0x1760080
	s_mov_b64 s[48:49], 0xe00100
	s_mov_b64 s[50:51], 0xe20100
	s_mov_b64 s[56:57], 0x1700100
	s_mov_b64 s[58:59], 0x1720100
	s_mov_b64 s[60:61], 0xe40100
	s_mov_b64 s[72:73], 0xe60100
	s_mov_b64 s[74:75], 0x1740100
	s_mov_b64 s[76:77], 0x1760100
	s_mov_b64 s[78:79], 0xe00180
	s_mov_b64 s[80:81], 0xe20180
	s_mov_b64 s[82:83], 0x1700180
	s_mov_b64 s[84:85], 0x1720180
	s_mov_b64 s[86:87], 0xe40180
	s_mov_b64 s[88:89], 0xe60180
	s_movk_i32 s13, 0x210
	v_mov_b32_e32 v129, 0
	v_mov_b32_e32 v134, 0x10800
	v_mov_b32_e32 v135, 0x12900
	s_branch .Lkvm_240

; DI int otid() { int t = __builtin_amdgcn_workitem_id_x(); asm volatile("" : "+v"(t)); return t; }
; DI void mlstmA_item(const Params& p, char* lds, int item) {
;   char* ws = p.ws;
;   const int bh = item >> 7, c = item & 127, b = bh >> 2, hd = bh & 3;
;   const int tid = otid(), lane = tid & 63, wave = tid >> 6, hh = lane >> 5, l31 = lane & 31;
;   u16* KTs = (u16*)lds;
;   u16* VTs = KTs + 128 * 72;
;   float* win = (float*)(VTs + 128 * 72);
;   const u16* PM = (const u16*)(ws + OFF_PM); const u16* VTm = (const u16*)(ws + OFF_VTM);
;   const float* G = (const float*)(ws + OFF_G);
;   u16* KVS = (u16*)(ws + OFF_KVS) + (size_t)item * 16384; float* KSUM = (float*)(ws + OFF_KSUM) + (size_t)item * 128; float* CSC = (float*)(ws + OFF_CSC) + (size_t)item * 4;
; DI void phase_mixA(const Params& p, char* lds) {
;   for (int it = blockIdx.x; it < 4096; it += gridDim.x) mlstmA_item(p, lds, it);
.Lkvm_exit:
	s_mov_b32 s82, s53
	v_readlane_b32 s52, v250, 19
	v_readlane_b32 s59, v250, 17
	v_readlane_b32 s58, v250, 18
	s_mov_b32 s83, s2
	v_readlane_b32 s53, v250, 20
	s_cmp_lt_u32 s94, 64
	s_cselect_b32 s99, 64, 0xc0
	s_cselect_b32 s100, 0x280, 0
	s_cselect_b32 s98, 0xdc0, 0
	s_addk_i32 s100, 0xd80
	s_add_i32 s98, s98, s94
	s_sub_i32 s98, s98, 64
	s_cmp_ge_i32 s98, s100
	s_cbranch_scc1 .LBB0_342
	s_add_u32 s4, s68, 0x16800000
	s_addc_u32 s5, s69, 0
	s_add_u32 s6, s68, 0x22800000
	s_addc_u32 s7, s69, 0
	s_add_u32 s2, s68, 0x32800000
	s_addc_u32 s16, s69, 0
	s_add_u32 s17, s68, 0x3a800000
	s_addc_u32 s20, s69, 0
	v_mbcnt_hi_u32_b32 v34, -1, v203
	s_add_u32 s21, s68, 0x3aa00000
	v_and_b32_e32 v35, 64, v34
	v_bfrev_b32_e32 v0, 0.5
	s_addc_u32 s22, s69, 0
	s_mov_b32 s9, 0
	s_mov_b32 s23, 0xbfb8aa3b
	v_mov_b32_e32 v32, 0x3ecc95a3
	v_mov_b32_e32 v17, 0
	s_movk_i32 s26, 0x90
	v_mov_b32_e32 v33, 0x7f800000
	v_add_u32_e32 v36, -1, v34
	v_add_u32_e32 v37, -2, v34
	v_add_u32_e32 v38, -4, v34
	v_add_u32_e32 v39, -8, v34
	v_add_u32_e32 v40, -16, v34
	v_subrev_u32_e32 v41, 32, v34
	v_add_u32_e32 v42, 64, v35
	v_xor_b32_e32 v43, 32, v34
	v_xor_b32_e32 v44, 16, v34
	v_xor_b32_e32 v45, 8, v34
	v_xor_b32_e32 v46, 4, v34
	v_xor_b32_e32 v47, 2, v34
	v_xor_b32_e32 v48, 1, v34
	v_lshl_or_b32 v49, v34, 2, v0
	s_mov_b32 s10, s98
	v_and_b32_e32 v19, 63, v222
	v_readfirstlane_b32 s81, v222
	s_nop 3
	s_lshr_b32 s81, s81, 6
	s_mov_b32 s80, 0
; DI float wmax(float v) { for (int o = 32; o; o >>= 1) v = fmaxf(v, __shfl_xor(v, o)); return v; }
; DI float scan_sum(float v, int lane) { for (int o = 1; o < 64; o <<= 1) { float tv = __shfl_up(v, o); if (lane >= o) v += tv; } return v; }
; DI float log_sigmoid(float f) { return fminf(f, 0.f) - log1pf(expf(-fabsf(f))); }
; DI void mlstmA_item(const Params& p, char* lds, int item) {
;     ...
;   if (wave == 0) {
;     const size_t row = (size_t)b * SEQ + c * 64 + lane;
;     const float ig = G[row * 8 + hd] + p.in[7][hd], fg = G[row * 8 + 4 + hd] + p.in[8][hd];
;     const float bc = scan_sum(log_sigmoid(fg), lane);
;     const float as = ig - bc;
;     const float gmax = wmax(as);
;     const float B = __shfl(bc, 63);
;     win[lane] = expf(as - gmax);
;     if (lane == 0) { CSC[0] = B; CSC[1] = B + gmax; }
;   }
.Lmg_round:
	s_lshl_b32 s32, s80, 3
	s_add_u32 s32, s32, s81
	s_mul_i32 s10, s32, s99
	s_add_i32 s10, s10, s98
	s_cmp_ge_i32 s10, s100
	s_cbranch_scc1 .Lmg_next
	s_lshl_b32 s32, s32, 8
	s_and_b32 s18, s10, 0x7f
	s_ashr_i32 s12, s10, 9
	s_bfe_u32 s27, s10, 0x20007
	s_ashr_i32 s11, s10, 31
	s_ashr_i32 s13, s12, 31
	s_lshl_b64 s[0:1], s[12:13], 13
	s_lshl_b32 s18, s18, 6
	v_or_b32_e32 v0, s0, v19
	v_or_b32_e32 v0, s18, v0
	v_mov_b32_e32 v1, s1
	v_lshlrev_b64 v[0:1], 5, v[0:1]
	v_lshl_add_u64 v[0:1], s[52:53], 0, v[0:1]
	s_lshl_b32 s8, s27, 2
	v_lshl_add_u64 v[2:3], v[0:1], 0, s[8:9]
	v_mov_b32_e32 v1, s8
	global_load_dword v0, v[2:3], off
	global_load_dword v4, v1, s[66:67]
	s_nop 0
	global_load_dword v2, v[2:3], off offset:16
	s_nop 0
	global_load_dword v1, v1, s[36:37]
	s_mov_b32 s0, 0xb2a5705f
	s_waitcnt vmcnt(2)
	v_add_f32_e32 v0, v0, v4
	s_waitcnt vmcnt(0)
	v_add_f32_e32 v1, v2, v1
	v_mul_f32_e64 v2, |v1|, s23
	v_fma_f32 v3, |v1|, s23, -v2
	v_rndne_f32_e32 v5, v2
	v_fma_f32 v3, |v1|, s0, v3
	v_sub_f32_e32 v2, v2, v5
	v_add_f32_e32 v2, v2, v3
	v_exp_f32_e32 v2, v2
	v_cvt_i32_f32_e32 v3, v5
	s_mov_b32 s0, 0x42ce8ed0
	v_cmp_ngt_f32_e64 vcc, |v1|, s0
	s_mov_b32 s0, 0xc2b17218
	v_ldexp_f32 v2, v2, v3
	v_cndmask_b32_e32 v2, 0, v2, vcc
	v_cmp_nlt_f32_e64 vcc, |v1|, s0
	v_min_f32_e32 v4, 0, v1
	s_mov_b32 s0, 0x3f2aaaab
	v_cndmask_b32_e32 v1, v33, v2, vcc
	v_add_f32_e32 v5, 1.0, v1
	v_add_f32_e32 v2, -1.0, v5
	v_sub_f32_e32 v3, v2, v5
	v_add_f32_e32 v3, 1.0, v3
	v_sub_f32_e32 v2, v1, v2
	v_add_f32_e32 v6, v2, v3
	v_frexp_mant_f32_e32 v2, v5
	v_cmp_gt_f32_e32 vcc, s0, v2
	v_cvt_f64_f32_e32 v[2:3], v5
	v_frexp_exp_i32_f64_e32 v2, v[2:3]
	v_subbrev_co_u32_e32 v2, vcc, 0, v2, vcc
	v_sub_u32_e32 v3, 0, v2
	v_ldexp_f32 v5, v5, v3
	v_ldexp_f32 v3, v6, v3
	v_add_f32_e32 v6, -1.0, v5
	v_add_f32_e32 v7, 1.0, v6
	v_sub_f32_e32 v7, v5, v7
	v_add_f32_e32 v7, v3, v7
	v_add_f32_e32 v8, v6, v7
	v_sub_f32_e32 v6, v6, v8
	v_add_f32_e32 v6, v7, v6
	v_add_f32_e32 v7, 1.0, v5
	v_add_f32_e32 v9, -1.0, v7
	v_sub_f32_e32 v5, v5, v9
	v_add_f32_e32 v3, v3, v5
	v_add_f32_e32 v5, v7, v3
	v_sub_f32_e32 v7, v7, v5
	v_add_f32_e32 v3, v3, v7
	v_rcp_f32_e32 v7, v5
	v_cvt_f32_i32_e32 v2, v2
	s_mov_b32 s0, 0x3f317218
	v_mul_f32_e32 v9, v8, v7
	v_mul_f32_e32 v10, v5, v9
	v_fma_f32 v11, v9, v5, -v10
	v_fmac_f32_e32 v11, v9, v3
	v_add_f32_e32 v12, v10, v11
	v_sub_f32_e32 v13, v8, v12
	v_sub_f32_e32 v8, v8, v13
	v_sub_f32_e32 v10, v12, v10
	v_sub_f32_e32 v8, v8, v12
	v_add_f32_e32 v6, v6, v8
	v_sub_f32_e32 v8, v10, v11
	v_add_f32_e32 v6, v8, v6
	v_add_f32_e32 v8, v13, v6
	v_mul_f32_e32 v10, v7, v8
	v_mul_f32_e32 v11, v5, v10
	v_fma_f32 v5, v10, v5, -v11
	v_fmac_f32_e32 v5, v10, v3
	v_sub_f32_e32 v3, v13, v8
	v_add_f32_e32 v3, v6, v3
	v_add_f32_e32 v6, v11, v5
	v_sub_f32_e32 v12, v8, v6
	v_sub_f32_e32 v8, v8, v12
	v_sub_f32_e32 v11, v6, v11
	v_sub_f32_e32 v6, v8, v6
	v_add_f32_e32 v3, v3, v6
	v_sub_f32_e32 v5, v11, v5
	v_add_f32_e32 v3, v5, v3
	v_add_f32_e32 v5, v9, v10
	v_add_f32_e32 v3, v12, v3
	v_sub_f32_e32 v6, v5, v9
	v_mul_f32_e32 v3, v7, v3
	v_sub_f32_e32 v6, v10, v6
	v_add_f32_e32 v3, v6, v3
	v_mul_f32_e32 v9, 0x3f317218, v2
	v_add_f32_e32 v6, v5, v3
	v_fma_f32 v10, v2, s0, -v9
	v_mul_f32_e32 v7, v6, v6
	v_fmac_f32_e32 v10, 0xb102e308, v2
	v_sub_f32_e32 v2, v6, v5
	v_fmamk_f32 v8, v7, 0x3e9b6dac, v32
	v_sub_f32_e32 v2, v3, v2
	v_add_f32_e32 v3, v9, v10
	v_fmaak_f32 v8, v7, v8, 0x3f2aaada
	v_sub_f32_e32 v5, v3, v9
	v_ldexp_f32 v9, v6, 1
	v_mul_f32_e32 v6, v6, v7
	v_mul_f32_e32 v6, v6, v8
	v_add_f32_e32 v7, v9, v6
	v_sub_f32_e32 v8, v7, v9
	v_ldexp_f32 v2, v2, 1
	v_sub_f32_e32 v6, v6, v8
	v_add_f32_e32 v2, v2, v6
	v_add_f32_e32 v6, v7, v2
	v_sub_f32_e32 v7, v6, v7
	v_sub_f32_e32 v2, v2, v7
	v_add_f32_e32 v7, v3, v6
	v_sub_f32_e32 v8, v7, v3
	v_sub_f32_e32 v9, v7, v8
	v_sub_f32_e32 v5, v10, v5
	v_sub_f32_e32 v3, v3, v9
	v_sub_f32_e32 v6, v6, v8
	v_add_f32_e32 v3, v6, v3
	v_add_f32_e32 v6, v5, v2
	v_sub_f32_e32 v8, v6, v5
	v_sub_f32_e32 v9, v6, v8
	v_sub_f32_e32 v5, v5, v9
	v_sub_f32_e32 v2, v2, v8
	v_add_f32_e32 v3, v6, v3
	v_add_f32_e32 v2, v2, v5
	v_add_f32_e32 v5, v7, v3
	v_sub_f32_e32 v6, v5, v7
	v_sub_f32_e32 v3, v3, v6
	v_add_f32_e32 v2, v2, v3
	s_mov_b32 s0, 0x7f800000
	v_add_f32_e32 v2, v5, v2
	v_cmp_neq_f32_e32 vcc, s0, v1
	s_mov_b32 s0, 0x33800000
	s_nop 0
	v_cndmask_b32_e32 v2, v33, v2, vcc
	v_cmp_lt_f32_e64 vcc, |v1|, s0
	s_nop 0
	v_cndmask_b32_e32 v1, v2, v1, vcc
	v_sub_f32_e32 v1, v4, v1
	s_nop 1
	v_add_f32_dpp v1, v1, v1 row_shr:1 row_mask:0xf bank_mask:0xf
	s_nop 1
	v_add_f32_dpp v1, v1, v1 row_shr:2 row_mask:0xf bank_mask:0xf
	s_nop 1
	v_add_f32_dpp v1, v1, v1 row_shr:4 row_mask:0xf bank_mask:0xf
	s_nop 1
	v_add_f32_dpp v1, v1, v1 row_shr:8 row_mask:0xf bank_mask:0xf
	s_nop 1
	v_add_f32_dpp v1, v1, v1 row_bcast:15 row_mask:0xa bank_mask:0xf
	s_nop 1
	v_add_f32_dpp v1, v1, v1 row_bcast:31 row_mask:0xc bank_mask:0xf
	v_sub_f32_e32 v3, v0, v1
	v_mov_b32_e32 v2, v1
	v_mov_b32_e32 v5, v3
	s_nop 1
	v_max_f32_dpp v5, v5, v5 row_shr:1 row_mask:0xf bank_mask:0xf
	s_nop 1
	v_max_f32_dpp v5, v5, v5 row_shr:2 row_mask:0xf bank_mask:0xf
	s_nop 1
	v_max_f32_dpp v5, v5, v5 row_shr:4 row_mask:0xf bank_mask:0xf
	s_nop 1
	v_max_f32_dpp v5, v5, v5 row_shr:8 row_mask:0xf bank_mask:0xf
	s_nop 1
	v_max_f32_dpp v5, v5, v5 row_bcast:15 row_mask:0xa bank_mask:0xf
	s_nop 1
	v_max_f32_dpp v5, v5, v5 row_bcast:31 row_mask:0xc bank_mask:0xf
	s_nop 0
	v_readlane_b32 s1, v5, 63
	v_readlane_b32 s30, v2, 63
	v_cmp_eq_u32_e32 vcc, 0, v19
	s_mov_b32 s0, 0x3fb8aa3b
	s_nop 0
	v_mov_b32_e32 v0, s30
	v_mov_b32_e32 v1, s1
	v_sub_f32_e32 v2, v3, v1
	v_mul_f32_e32 v3, 0x3fb8aa3b, v2
	v_fma_f32 v4, v2, s0, -v3
	v_rndne_f32_e32 v5, v3
	v_fmac_f32_e32 v4, 0x32a5705f, v2
	v_sub_f32_e32 v3, v3, v5
	v_add_f32_e32 v3, v3, v4
	v_exp_f32_e32 v3, v3
	v_cvt_i32_f32_e32 v4, v5
	s_mov_b32 s0, 0xc2ce8ed0
	v_cmp_ngt_f32_e64 s[0:1], s0, v2
	v_ldexp_f32 v3, v3, v4
	s_nop 0
	v_cndmask_b32_e64 v3, 0, v3, s[0:1]
	s_mov_b32 s0, 0x42b17218
	v_cmp_nlt_f32_e64 s[0:1], s0, v2
	s_nop 1
	v_cndmask_b32_e64 v2, v33, v3, s[0:1]
	v_lshl_add_u32 v3, v19, 2, s32
	ds_write_b32 v3, v2 offset:40960
	s_and_saveexec_b64 s[0:1], vcc
	s_cbranch_execz .Lmg_skipst
	s_lshl_b64 s[30:31], s[10:11], 4
	s_add_u32 s30, s21, s30
	s_addc_u32 s31, s22, s31
	s_waitcnt lgkmcnt(1)
	v_add_f32_e32 v1, v1, v0
	global_store_dwordx2 v17, v[0:1], s[30:31]

; DI u16 f2bf(float x) { return (u16)(pack2(x, 0.f) & 0xffffu); }
; DI void mlstmA_item(const Params& p, char* lds, int item) {
;     ...
;   for (int i = 0; i < 2; ++i) {
;     const int q = tid + 512 * i, e = q >> 3, s8 = (q & 7) * 8;
;     *(uint4*)(VTs + e * 72 + s8) = *(const uint4*)(VTm + ((size_t)(bh * 128 + e)) * SEQ + c * 64 + s8);
;   }
;   __syncthreads();
; #pragma unroll 1
;   for (int i = 0; i < 2; ++i) {
;     const int cgk = tid & 15, t = (tid >> 4) + 32 * i;
;     float a8[8];
;     conv_unit(PM, p.in[5], p.in[6], b, c * 64 + t, 512 + hd * 128 + cgk * 8, 0.08838834764831845f, a8);
;     const float w = win[t];
; #pragma unroll
;     for (int e = 0; e < 8; ++e) KTs[(cgk * 8 + e) * 72 + t] = f2bf(a8[e] * w);
; DI void phase_mixA(const Params& p, char* lds) {
;   for (int it = blockIdx.x; it < 4096; it += gridDim.x) mlstmA_item(p, lds, it);
.Lmg_next:
	s_add_i32 s80, s80, 1
	s_cmp_lt_u32 s80, 3
	s_cbranch_scc1 .Lmg_round
	s_mov_b32 s10, s98
	s_mov_b32 s96, 0
	v_add_u32_e32 v240, 0x200, v222
	s_and_b32 s73, s10, 0xffffff80
	v_lshlrev_b32_e32 v241, 4, v222
	v_ashrrev_i32_e32 v242, 3, v222
	v_ashrrev_i32_e32 v244, 3, v240
	v_and_b32_e32 v246, 0x70, v241
	v_mov_b32_e32 v247, 0
	v_add_u32_e32 v242, s73, v242
	v_add_u32_e32 v244, s73, v244
	s_and_b32 s78, s10, 0x7f
	s_lshl_b32 s78, s78, 7
	v_mov_b32_e32 v248, s78
	v_mov_b32_e32 v249, 0
	v_lshl_add_u64 v[248:249], s[6:7], 0, v[248:249]
	v_lshl_add_u64 v[248:249], v[248:249], 0, v[246:247]
	v_ashrrev_i32_e32 v243, 31, v242
	v_ashrrev_i32_e32 v245, 31, v244
	v_lshlrev_b64 v[242:243], 14, v[242:243]
	v_lshlrev_b64 v[244:245], 14, v[244:245]
	v_lshl_add_u64 v[242:243], v[248:249], 0, v[242:243]
	v_lshl_add_u64 v[244:245], v[248:249], 0, v[244:245]
	global_load_dwordx4 v[232:235], v[242:243], off
	global_load_dwordx4 v[236:239], v[244:245], off
	v_and_b32_e32 v70, 15, v222
	s_bfe_u32 s72, s10, 0x20007
	v_lshlrev_b32_e32 v70, 3, v70
	s_lshl_b32 s72, s72, 7
	v_add_u32_e32 v70, s72, v70
	s_ashr_i32 s74, s10, 9
	s_ashr_i32 s75, s74, 31
	s_lshl_b64 s[74:75], s[74:75], 24
	s_add_u32 s74, s74, s4
	s_addc_u32 s75, s75, s5
	v_lshlrev_b32_e32 v76, 1, v70
	v_mov_b32_e32 v77, 0
	v_lshl_add_u64 v[78:79], s[74:75], 0, v[76:77]
	s_and_b32 s76, s10, 0x7f
	s_lshl_b32 s76, s76, 6
	v_lshrrev_b32_e32 v75, 4, v222
	s_movk_i32 s77, 0x800
	v_add_u32_e32 v184, s76, v75
	v_add_u32_e32 v185, -1, v184
	v_mov_b32_e32 v114, 0
	v_mov_b32_e32 v115, 0
	v_mov_b32_e32 v116, 0
	v_mov_b32_e32 v117, 0
	v_mov_b32_e32 v118, 0
	v_mov_b32_e32 v119, 0
	v_mov_b32_e32 v120, 0
	v_mov_b32_e32 v121, 0
	v_mov_b32_e32 v122, 0
	v_mov_b32_e32 v123, 0
	v_mov_b32_e32 v124, 0
	v_mov_b32_e32 v125, 0
	v_mad_i64_i32 v[186:187], s[88:89], v185, s77, v[78:79]
	v_cmp_lt_i32_e64 s[84:85], 2, v184
	s_and_saveexec_b64 s[86:87], s[84:85]
	global_load_dwordx4 v[114:117], v[186:187], off offset:-3072
	s_or_b64 exec, exec, s[86:87]
	v_cmp_lt_i32_e64 s[84:85], 1, v184
	s_and_saveexec_b64 s[86:87], s[84:85]
	global_load_dwordx4 v[118:121], v[186:187], off offset:-1024
	s_or_b64 exec, exec, s[86:87]
	v_cmp_lt_i32_e64 s[84:85], 0, v184
	s_and_saveexec_b64 s[86:87], s[84:85]
	global_load_dwordx4 v[122:125], v[186:187], off offset:1024
	s_or_b64 exec, exec, s[86:87]
	global_load_dwordx4 v[126:129], v[186:187], off offset:3072
	v_add_u32_e32 v184, 32, v184
	v_add_u32_e32 v185, -1, v184
	v_mov_b32_e32 v130, 0
	v_mov_b32_e32 v131, 0
	v_mov_b32_e32 v132, 0
	v_mov_b32_e32 v133, 0
	v_mov_b32_e32 v134, 0
	v_mov_b32_e32 v135, 0
	v_mov_b32_e32 v136, 0
	v_mov_b32_e32 v137, 0
	v_mov_b32_e32 v172, 0
	v_mov_b32_e32 v173, 0
	v_mov_b32_e32 v174, 0
	v_mov_b32_e32 v175, 0
	v_mad_i64_i32 v[186:187], s[88:89], v185, s77, v[78:79]
	v_cmp_lt_i32_e64 s[84:85], 2, v184
	s_and_saveexec_b64 s[86:87], s[84:85]
	global_load_dwordx4 v[130:133], v[186:187], off offset:-3072
	s_or_b64 exec, exec, s[86:87]
	v_cmp_lt_i32_e64 s[84:85], 1, v184
	s_and_saveexec_b64 s[86:87], s[84:85]
	global_load_dwordx4 v[134:137], v[186:187], off offset:-1024
	s_or_b64 exec, exec, s[86:87]
	v_cmp_lt_i32_e64 s[84:85], 0, v184
	s_and_saveexec_b64 s[86:87], s[84:85]
	global_load_dwordx4 v[172:175], v[186:187], off offset:1024
	s_or_b64 exec, exec, s[86:87]
	global_load_dwordx4 v[176:179], v[186:187], off offset:3072
	s_waitcnt vmcnt(0)
	s_branch .LBB0_324
.LBB0_323:
	s_or_b64 exec, exec, s[0:1]
	s_add_i32 s10, s10, s99
	s_add_i32 s96, s96, 0x100
	s_cmp_ge_i32 s10, s100
	s_barrier
	s_cbranch_scc1 .LBB0_342

; DI u16 f2bf(float x) { return (u16)(pack2(x, 0.f) & 0xffffu); }
; DI void conv_unit(const u16* __restrict__ PM, const float* __restrict__ conv_w, const float* __restrict__ conv_b, int b, int sl0, int ch, float scale, float* a8) {
;   { const float4 b0 = *(const float4*)(conv_b + ch), b1 = *(const float4*)(conv_b + ch + 4); a8[0] = b0.x; a8[1] = b0.y; a8[2] = b0.z; a8[3] = b0.w; a8[4] = b1.x; a8[5] = b1.y; a8[6] = b1.z; a8[7] = b1.w; }
; #pragma unroll
;   for (int j = 0; j < 4; ++j) {
;     const int sl = sl0 - 3 + j;
;     if (sl >= 0) {
;       const uint4 raw = *(const uint4*)(PM + ((size_t)b * SEQ + sl) * 1024 + ch);
;       float x8[8]; unpack8(raw, x8);
;       const float4 w0 = *(const float4*)(conv_w + j * 1024 + ch), w1 = *(const float4*)(conv_w + j * 1024 + ch + 4);
;       a8[0] += w0.x * x8[0]; a8[1] += w0.y * x8[1]; a8[2] += w0.z * x8[2]; a8[3] += w0.w * x8[3];
;       a8[4] += w1.x * x8[4]; a8[5] += w1.y * x8[5]; a8[6] += w1.z * x8[6]; a8[7] += w1.w * x8[7];
;     }
;   }
; #pragma unroll
;   for (int e = 0; e < 8; ++e) { const float v = a8[e]; a8[e] = scale * v * __builtin_amdgcn_rcpf(1.f + __expf(-v)); }
; }
; DI void mlstmA_item(const Params& p, char* lds, int item) {
;     ...
;   for (int i = 0; i < 2; ++i) {
;     const int q = tid + 512 * i, e = q >> 3, s8 = (q & 7) * 8;
;     *(uint4*)(VTs + e * 72 + s8) = *(const uint4*)(VTm + ((size_t)(bh * 128 + e)) * SEQ + c * 64 + s8);
;   }
;   __syncthreads();
; #pragma unroll 1
;   for (int i = 0; i < 2; ++i) {
;     const int cgk = tid & 15, t = (tid >> 4) + 32 * i;
;     float a8[8];
;     conv_unit(PM, p.in[5], p.in[6], b, c * 64 + t, 512 + hd * 128 + cgk * 8, 0.08838834764831845f, a8);
;     const float w = win[t];
; #pragma unroll
;     for (int e = 0; e < 8; ++e) KTs[(cgk * 8 + e) * 72 + t] = f2bf(a8[e] * w);
.LBB0_330:
	s_or_b64 exec, exec, s[14:15]
	v_add_u32_e32 v4, 0x200, v18
	s_and_b32 s0, s10, 0xffffff80
	v_lshlrev_b32_e32 v2, 4, v18
	v_ashrrev_i32_e32 v9, 3, v18
	v_ashrrev_i32_e32 v14, 3, v4
	v_and_b32_e32 v16, 0x70, v2
	v_add_u32_e32 v2, s0, v9
	v_add_u32_e32 v4, s0, v14
	v_lshl_add_u64 v[0:1], v[0:1], 1, s[6:7]
	v_ashrrev_i32_e32 v3, 31, v2
	v_ashrrev_i32_e32 v5, 31, v4
	v_lshl_add_u64 v[0:1], v[0:1], 0, v[16:17]
	v_lshlrev_b64 v[2:3], 14, v[2:3]
	v_lshlrev_b64 v[4:5], 14, v[4:5]
	v_lshl_add_u64 v[2:3], v[0:1], 0, v[2:3]
	v_lshl_add_u64 v[4:5], v[0:1], 0, v[4:5]
	v_lshlrev_b32_e32 v8, 3, v18
	v_and_b32_e32 v22, 0x78, v8
	v_add_u32_e32 v8, 0, v16
	v_lshl_or_b32 v15, s27, 7, v22
	v_mad_u64_u32 v[12:13], s[0:1], v9, s26, v[8:9]
	v_lshlrev_b32_e32 v16, 2, v15
	v_mad_u64_u32 v[8:9], s[0:1], v14, s26, v[8:9]
	v_lshlrev_b64 v[10:11], 24, v[10:11]
	v_lshl_add_u64 v[10:11], s[4:5], 0, v[10:11]
	v_mov_b32_e32 v13, v17
	s_mov_b64 s[0:1], 0x1800
	v_ashrrev_i32_e32 v51, 4, v18
	v_mad_u32_u24 v52, v22, s26, 0
	s_mov_b32 s8, 0
	s_waitcnt vmcnt(20)
	ds_write_b128 v12, v[232:235] offset:18432
	ds_write_b128 v8, v[236:239] offset:18432
	s_waitcnt lgkmcnt(0)
	s_barrier
	s_add_i32 s97, s10, s99
	v_add_u32_e32 v240, 0x200, v222
	s_and_b32 s73, s97, 0xffffff80
	v_lshlrev_b32_e32 v241, 4, v222
	v_ashrrev_i32_e32 v242, 3, v222
	v_ashrrev_i32_e32 v244, 3, v240
	v_and_b32_e32 v246, 0x70, v241
	v_mov_b32_e32 v247, 0
	v_add_u32_e32 v242, s73, v242
	v_add_u32_e32 v244, s73, v244
	s_and_b32 s78, s97, 0x7f
	s_lshl_b32 s78, s78, 7
	v_mov_b32_e32 v248, s78
	v_mov_b32_e32 v249, 0
	v_lshl_add_u64 v[248:249], s[6:7], 0, v[248:249]
	v_lshl_add_u64 v[248:249], v[248:249], 0, v[246:247]
	v_ashrrev_i32_e32 v243, 31, v242
	v_ashrrev_i32_e32 v245, 31, v244
	v_lshlrev_b64 v[242:243], 14, v[242:243]
	v_lshlrev_b64 v[244:245], 14, v[244:245]
	v_lshl_add_u64 v[242:243], v[248:249], 0, v[242:243]
	v_lshl_add_u64 v[244:245], v[248:249], 0, v[244:245]
	global_load_dwordx4 v[232:235], v[242:243], off
	global_load_dwordx4 v[236:239], v[244:245], off
	s_waitcnt vmcnt(2)
	v_mov_b32_e32 v197, v51
	v_lshl_add_u32 v196, v197, 2, s96
	ds_read_b32 v196, v196 offset:40960
	v_lshl_add_u32 v198, v197, 1, v52
	v_lshlrev_b32_e32 v188, 16, v114
	v_and_b32_e32 v189, 0xffff0000, v114
	v_lshlrev_b32_e32 v190, 16, v115
	v_and_b32_e32 v191, 0xffff0000, v115
	v_lshlrev_b32_e32 v192, 16, v116
	v_and_b32_e32 v193, 0xffff0000, v116
	v_lshlrev_b32_e32 v194, 16, v117
	v_and_b32_e32 v195, 0xffff0000, v117
	v_pk_fma_f32 v[204:205], v[140:141], v[188:189], v[224:225]
	v_pk_fma_f32 v[206:207], v[142:143], v[190:191], v[226:227]
	v_pk_fma_f32 v[208:209], v[144:145], v[192:193], v[228:229]
	v_pk_fma_f32 v[210:211], v[146:147], v[194:195], v[230:231]
	v_lshlrev_b32_e32 v188, 16, v118
	v_and_b32_e32 v189, 0xffff0000, v118
	v_lshlrev_b32_e32 v190, 16, v119
	v_and_b32_e32 v191, 0xffff0000, v119
	v_lshlrev_b32_e32 v192, 16, v120
	v_and_b32_e32 v193, 0xffff0000, v120
	v_lshlrev_b32_e32 v194, 16, v121
	v_and_b32_e32 v195, 0xffff0000, v121
	v_pk_fma_f32 v[204:205], v[148:149], v[188:189], v[204:205]
	v_pk_fma_f32 v[206:207], v[150:151], v[190:191], v[206:207]
	v_pk_fma_f32 v[208:209], v[152:153], v[192:193], v[208:209]
	v_pk_fma_f32 v[210:211], v[154:155], v[194:195], v[210:211]
	v_lshlrev_b32_e32 v188, 16, v122
	v_and_b32_e32 v189, 0xffff0000, v122
	v_lshlrev_b32_e32 v190, 16, v123
	v_and_b32_e32 v191, 0xffff0000, v123
	v_lshlrev_b32_e32 v192, 16, v124
	v_and_b32_e32 v193, 0xffff0000, v124
	v_lshlrev_b32_e32 v194, 16, v125
	v_and_b32_e32 v195, 0xffff0000, v125
	v_pk_fma_f32 v[204:205], v[156:157], v[188:189], v[204:205]
	v_pk_fma_f32 v[206:207], v[158:159], v[190:191], v[206:207]
	v_pk_fma_f32 v[208:209], v[160:161], v[192:193], v[208:209]
	v_pk_fma_f32 v[210:211], v[162:163], v[194:195], v[210:211]
	v_lshlrev_b32_e32 v188, 16, v126
	v_and_b32_e32 v189, 0xffff0000, v126
	v_lshlrev_b32_e32 v190, 16, v127
	v_and_b32_e32 v191, 0xffff0000, v127
	v_lshlrev_b32_e32 v192, 16, v128
	v_and_b32_e32 v193, 0xffff0000, v128
	v_lshlrev_b32_e32 v194, 16, v129
	v_and_b32_e32 v195, 0xffff0000, v129
	v_pk_fma_f32 v[204:205], v[164:165], v[188:189], v[204:205]
	v_pk_fma_f32 v[206:207], v[166:167], v[190:191], v[206:207]
	v_pk_fma_f32 v[208:209], v[168:169], v[192:193], v[208:209]
	v_pk_fma_f32 v[210:211], v[170:171], v[194:195], v[210:211]
	v_mul_f32_e32 v212, 0xbfb8aa3b, v204
	v_mul_f32_e32 v213, 0xbfb8aa3b, v205
	v_mul_f32_e32 v214, 0xbfb8aa3b, v206
	v_mul_f32_e32 v215, 0xbfb8aa3b, v207
	v_mul_f32_e32 v216, 0xbfb8aa3b, v208
	v_mul_f32_e32 v217, 0xbfb8aa3b, v209
	v_mul_f32_e32 v218, 0xbfb8aa3b, v210
	v_mul_f32_e32 v219, 0xbfb8aa3b, v211
	v_mul_f32_e32 v188, 0x3db504f3, v204
	v_mul_f32_e32 v189, 0x3db504f3, v205
	v_mul_f32_e32 v190, 0x3db504f3, v206
	v_mul_f32_e32 v191, 0x3db504f3, v207
	v_mul_f32_e32 v192, 0x3db504f3, v208
	v_mul_f32_e32 v193, 0x3db504f3, v209
	v_mul_f32_e32 v194, 0x3db504f3, v210
	v_mul_f32_e32 v195, 0x3db504f3, v211
	v_exp_f32_e32 v212, v212
	v_exp_f32_e32 v213, v213
	v_exp_f32_e32 v214, v214
	v_exp_f32_e32 v215, v215
	v_exp_f32_e32 v216, v216
	v_exp_f32_e32 v217, v217
	v_exp_f32_e32 v218, v218
	v_exp_f32_e32 v219, v219
	v_add_f32_e32 v212, 1.0, v212
	v_add_f32_e32 v213, 1.0, v213
	v_add_f32_e32 v214, 1.0, v214
	v_add_f32_e32 v215, 1.0, v215
	v_add_f32_e32 v216, 1.0, v216
	v_add_f32_e32 v217, 1.0, v217
	v_add_f32_e32 v218, 1.0, v218
	v_add_f32_e32 v219, 1.0, v219
	v_rcp_f32_e32 v212, v212
	v_rcp_f32_e32 v213, v213
	v_rcp_f32_e32 v214, v214
	v_rcp_f32_e32 v215, v215
	v_rcp_f32_e32 v216, v216
	v_rcp_f32_e32 v217, v217
	v_rcp_f32_e32 v218, v218
	v_rcp_f32_e32 v219, v219
	v_mul_f32_e32 v188, v188, v212
	v_mul_f32_e32 v189, v189, v213
	v_mul_f32_e32 v190, v190, v214
	v_mul_f32_e32 v191, v191, v215
	v_mul_f32_e32 v192, v192, v216
	v_mul_f32_e32 v193, v193, v217
	v_mul_f32_e32 v194, v194, v218
	v_mul_f32_e32 v195, v195, v219
	s_waitcnt lgkmcnt(0)
; DI u16 f2bf(float x) { return (u16)(pack2(x, 0.f) & 0xffffu); }
; DI void conv_unit(const u16* __restrict__ PM, const float* __restrict__ conv_w, const float* __restrict__ conv_b, int b, int sl0, int ch, float scale, float* a8) {
;     ...
;       a8[0] += w0.x * x8[0]; a8[1] += w0.y * x8[1]; a8[2] += w0.z * x8[2]; a8[3] += w0.w * x8[3];
;       a8[4] += w1.x * x8[4]; a8[5] += w1.y * x8[5]; a8[6] += w1.z * x8[6]; a8[7] += w1.w * x8[7];
;     }
;   }
; #pragma unroll
;   for (int e = 0; e < 8; ++e) { const float v = a8[e]; a8[e] = scale * v * __builtin_amdgcn_rcpf(1.f + __expf(-v)); }
; DI void mlstmA_item(const Params& p, char* lds, int item) {
;     ...
;     conv_unit(PM, p.in[5], p.in[6], b, c * 64 + t, 512 + hd * 128 + cgk * 8, 0.08838834764831845f, a8);
;     const float w = win[t];
; #pragma unroll
;     for (int e = 0; e < 8; ++e) KTs[(cgk * 8 + e) * 72 + t] = f2bf(a8[e] * w);
	v_mul_f32_e32 v188, v196, v188
	v_mul_f32_e32 v189, v196, v189
	v_mul_f32_e32 v190, v196, v190
	v_mul_f32_e32 v191, v196, v191
	v_mul_f32_e32 v192, v196, v192
	v_mul_f32_e32 v193, v196, v193
	v_mul_f32_e32 v194, v196, v194
	v_mul_f32_e32 v195, v196, v195
	v_cvt_pk_bf16_f32 v188, v188, s77
	v_cvt_pk_bf16_f32 v189, v189, s77
	v_cvt_pk_bf16_f32 v190, v190, s77
	v_cvt_pk_bf16_f32 v191, v191, s77
	v_cvt_pk_bf16_f32 v192, v192, s77
	v_cvt_pk_bf16_f32 v193, v193, s77
	v_cvt_pk_bf16_f32 v194, v194, s77
	v_cvt_pk_bf16_f32 v195, v195, s77
	ds_write_b16 v198, v188
	ds_write_b16 v198, v189 offset:144
	ds_write_b16 v198, v190 offset:288
	ds_write_b16 v198, v191 offset:432
	ds_write_b16 v198, v192 offset:576
	ds_write_b16 v198, v193 offset:720
	ds_write_b16 v198, v194 offset:864
	ds_write_b16 v198, v195 offset:1008
	v_add_u32_e32 v197, 32, v51
	v_lshl_add_u32 v196, v197, 2, s96
	ds_read_b32 v196, v196 offset:40960
	v_lshl_add_u32 v198, v197, 1, v52
	v_lshlrev_b32_e32 v188, 16, v130
	v_and_b32_e32 v189, 0xffff0000, v130
	v_lshlrev_b32_e32 v190, 16, v131
	v_and_b32_e32 v191, 0xffff0000, v131
	v_lshlrev_b32_e32 v192, 16, v132
	v_and_b32_e32 v193, 0xffff0000, v132
	v_lshlrev_b32_e32 v194, 16, v133
	v_and_b32_e32 v195, 0xffff0000, v133
	v_pk_fma_f32 v[204:205], v[140:141], v[188:189], v[224:225]
	v_pk_fma_f32 v[206:207], v[142:143], v[190:191], v[226:227]
	v_pk_fma_f32 v[208:209], v[144:145], v[192:193], v[228:229]
	v_pk_fma_f32 v[210:211], v[146:147], v[194:195], v[230:231]
	v_lshlrev_b32_e32 v188, 16, v134
	v_and_b32_e32 v189, 0xffff0000, v134
	v_lshlrev_b32_e32 v190, 16, v135
	v_and_b32_e32 v191, 0xffff0000, v135
	v_lshlrev_b32_e32 v192, 16, v136
	v_and_b32_e32 v193, 0xffff0000, v136
	v_lshlrev_b32_e32 v194, 16, v137
	v_and_b32_e32 v195, 0xffff0000, v137
	v_pk_fma_f32 v[204:205], v[148:149], v[188:189], v[204:205]
	v_pk_fma_f32 v[206:207], v[150:151], v[190:191], v[206:207]
	v_pk_fma_f32 v[208:209], v[152:153], v[192:193], v[208:209]
	v_pk_fma_f32 v[210:211], v[154:155], v[194:195], v[210:211]
	v_lshlrev_b32_e32 v188, 16, v172
	v_and_b32_e32 v189, 0xffff0000, v172
	v_lshlrev_b32_e32 v190, 16, v173
	v_and_b32_e32 v191, 0xffff0000, v173
	v_lshlrev_b32_e32 v192, 16, v174
	v_and_b32_e32 v193, 0xffff0000, v174
	v_lshlrev_b32_e32 v194, 16, v175
	v_and_b32_e32 v195, 0xffff0000, v175
	v_pk_fma_f32 v[204:205], v[156:157], v[188:189], v[204:205]
	v_pk_fma_f32 v[206:207], v[158:159], v[190:191], v[206:207]
	v_pk_fma_f32 v[208:209], v[160:161], v[192:193], v[208:209]
	v_pk_fma_f32 v[210:211], v[162:163], v[194:195], v[210:211]
	v_lshlrev_b32_e32 v188, 16, v176
	v_and_b32_e32 v189, 0xffff0000, v176
	v_lshlrev_b32_e32 v190, 16, v177
	v_and_b32_e32 v191, 0xffff0000, v177
	v_lshlrev_b32_e32 v192, 16, v178
	v_and_b32_e32 v193, 0xffff0000, v178
	v_lshlrev_b32_e32 v194, 16, v179
	v_and_b32_e32 v195, 0xffff0000, v179
	v_pk_fma_f32 v[204:205], v[164:165], v[188:189], v[204:205]
	v_pk_fma_f32 v[206:207], v[166:167], v[190:191], v[206:207]
	v_pk_fma_f32 v[208:209], v[168:169], v[192:193], v[208:209]
	v_pk_fma_f32 v[210:211], v[170:171], v[194:195], v[210:211]
	v_mul_f32_e32 v212, 0xbfb8aa3b, v204
	v_mul_f32_e32 v213, 0xbfb8aa3b, v205
	v_mul_f32_e32 v214, 0xbfb8aa3b, v206
	v_mul_f32_e32 v215, 0xbfb8aa3b, v207
	v_mul_f32_e32 v216, 0xbfb8aa3b, v208
	v_mul_f32_e32 v217, 0xbfb8aa3b, v209
	v_mul_f32_e32 v218, 0xbfb8aa3b, v210
	v_mul_f32_e32 v219, 0xbfb8aa3b, v211
	v_mul_f32_e32 v188, 0x3db504f3, v204
	v_mul_f32_e32 v189, 0x3db504f3, v205
	v_mul_f32_e32 v190, 0x3db504f3, v206
	v_mul_f32_e32 v191, 0x3db504f3, v207
	v_mul_f32_e32 v192, 0x3db504f3, v208
	v_mul_f32_e32 v193, 0x3db504f3, v209
	v_mul_f32_e32 v194, 0x3db504f3, v210
	v_mul_f32_e32 v195, 0x3db504f3, v211
	v_exp_f32_e32 v212, v212
	v_exp_f32_e32 v213, v213
	v_exp_f32_e32 v214, v214
	v_exp_f32_e32 v215, v215
	v_exp_f32_e32 v216, v216
	v_exp_f32_e32 v217, v217
	v_exp_f32_e32 v218, v218
	v_exp_f32_e32 v219, v219
	v_add_f32_e32 v212, 1.0, v212
	v_add_f32_e32 v213, 1.0, v213
	v_add_f32_e32 v214, 1.0, v214
	v_add_f32_e32 v215, 1.0, v215
	v_add_f32_e32 v216, 1.0, v216
	v_add_f32_e32 v217, 1.0, v217
	v_add_f32_e32 v218, 1.0, v218
	v_add_f32_e32 v219, 1.0, v219
	v_rcp_f32_e32 v212, v212
	v_rcp_f32_e32 v213, v213
	v_rcp_f32_e32 v214, v214
	v_rcp_f32_e32 v215, v215
	v_rcp_f32_e32 v216, v216
	v_rcp_f32_e32 v217, v217
	v_rcp_f32_e32 v218, v218
	v_rcp_f32_e32 v219, v219
	v_mul_f32_e32 v188, v188, v212
	v_mul_f32_e32 v189, v189, v213
	v_mul_f32_e32 v190, v190, v214
	v_mul_f32_e32 v191, v191, v215
	v_mul_f32_e32 v192, v192, v216
	v_mul_f32_e32 v193, v193, v217
	v_mul_f32_e32 v194, v194, v218
	v_mul_f32_e32 v195, v195, v219
	s_waitcnt lgkmcnt(0)
; DI u16 f2bf(float x) { return (u16)(pack2(x, 0.f) & 0xffffu); }
; DI void conv_unit(const u16* __restrict__ PM, const float* __restrict__ conv_w, const float* __restrict__ conv_b, int b, int sl0, int ch, float scale, float* a8) {
;   { const float4 b0 = *(const float4*)(conv_b + ch), b1 = *(const float4*)(conv_b + ch + 4); a8[0] = b0.x; a8[1] = b0.y; a8[2] = b0.z; a8[3] = b0.w; a8[4] = b1.x; a8[5] = b1.y; a8[6] = b1.z; a8[7] = b1.w; }
; #pragma unroll
;   for (int j = 0; j < 4; ++j) {
;     const int sl = sl0 - 3 + j;
;     if (sl >= 0) {
;       const uint4 raw = *(const uint4*)(PM + ((size_t)b * SEQ + sl) * 1024 + ch);
;       float x8[8]; unpack8(raw, x8);
;       const float4 w0 = *(const float4*)(conv_w + j * 1024 + ch), w1 = *(const float4*)(conv_w + j * 1024 + ch + 4);
; DI void mlstmA_item(const Params& p, char* lds, int item) {
;     ...
;     conv_unit(PM, p.in[5], p.in[6], b, c * 64 + t, 512 + hd * 128 + cgk * 8, 0.08838834764831845f, a8);
;     const float w = win[t];
; #pragma unroll
;     for (int e = 0; e < 8; ++e) KTs[(cgk * 8 + e) * 72 + t] = f2bf(a8[e] * w);
	v_mul_f32_e32 v188, v196, v188
	v_mul_f32_e32 v189, v196, v189
	v_mul_f32_e32 v190, v196, v190
	v_mul_f32_e32 v191, v196, v191
	v_mul_f32_e32 v192, v196, v192
	v_mul_f32_e32 v193, v196, v193
	v_mul_f32_e32 v194, v196, v194
	v_mul_f32_e32 v195, v196, v195
	v_cvt_pk_bf16_f32 v188, v188, s77
	v_cvt_pk_bf16_f32 v189, v189, s77
	v_cvt_pk_bf16_f32 v190, v190, s77
	v_cvt_pk_bf16_f32 v191, v191, s77
	v_cvt_pk_bf16_f32 v192, v192, s77
	v_cvt_pk_bf16_f32 v193, v193, s77
	v_cvt_pk_bf16_f32 v194, v194, s77
	v_cvt_pk_bf16_f32 v195, v195, s77
	ds_write_b16 v198, v188
	ds_write_b16 v198, v189 offset:144
	ds_write_b16 v198, v190 offset:288
	ds_write_b16 v198, v191 offset:432
	ds_write_b16 v198, v192 offset:576
	ds_write_b16 v198, v193 offset:720
	ds_write_b16 v198, v194 offset:864
	ds_write_b16 v198, v195 offset:1008
	s_add_i32 s97, s10, s99
	v_and_b32_e32 v70, 15, v222
	s_bfe_u32 s72, s97, 0x20007
	v_lshlrev_b32_e32 v70, 3, v70
	s_lshl_b32 s72, s72, 7
	v_add_u32_e32 v70, s72, v70
	s_ashr_i32 s74, s97, 9
	s_ashr_i32 s75, s74, 31
	s_lshl_b64 s[74:75], s[74:75], 24
	s_add_u32 s74, s74, s4
	s_addc_u32 s75, s75, s5
	v_lshlrev_b32_e32 v76, 1, v70
	v_mov_b32_e32 v77, 0
	v_lshl_add_u64 v[78:79], s[74:75], 0, v[76:77]
	s_and_b32 s76, s97, 0x7f
	s_lshl_b32 s76, s76, 6
	v_lshrrev_b32_e32 v75, 4, v222
	s_movk_i32 s77, 0x800
	v_add_u32_e32 v184, s76, v75
	v_add_u32_e32 v185, -1, v184
	v_mov_b32_e32 v114, 0
	v_mov_b32_e32 v115, 0
	v_mov_b32_e32 v116, 0
	v_mov_b32_e32 v117, 0
	v_mov_b32_e32 v118, 0
	v_mov_b32_e32 v119, 0
	v_mov_b32_e32 v120, 0
	v_mov_b32_e32 v121, 0
	v_mov_b32_e32 v122, 0
	v_mov_b32_e32 v123, 0
	v_mov_b32_e32 v124, 0
	v_mov_b32_e32 v125, 0
	v_mad_i64_i32 v[186:187], s[88:89], v185, s77, v[78:79]
	v_cmp_lt_i32_e64 s[84:85], 2, v184
	s_and_saveexec_b64 s[86:87], s[84:85]
	global_load_dwordx4 v[114:117], v[186:187], off offset:-3072
	s_or_b64 exec, exec, s[86:87]
	v_cmp_lt_i32_e64 s[84:85], 1, v184
	s_and_saveexec_b64 s[86:87], s[84:85]
	global_load_dwordx4 v[118:121], v[186:187], off offset:-1024
	s_or_b64 exec, exec, s[86:87]
	v_cmp_lt_i32_e64 s[84:85], 0, v184
	s_and_saveexec_b64 s[86:87], s[84:85]
	global_load_dwordx4 v[122:125], v[186:187], off offset:1024
	s_or_b64 exec, exec, s[86:87]
	global_load_dwordx4 v[126:129], v[186:187], off offset:3072
	v_add_u32_e32 v184, 32, v184
	v_add_u32_e32 v185, -1, v184
	v_mov_b32_e32 v130, 0
	v_mov_b32_e32 v131, 0
	v_mov_b32_e32 v132, 0
	v_mov_b32_e32 v133, 0
	v_mov_b32_e32 v134, 0
	v_mov_b32_e32 v135, 0
	v_mov_b32_e32 v136, 0
	v_mov_b32_e32 v137, 0
	v_mov_b32_e32 v172, 0
	v_mov_b32_e32 v173, 0
	v_mov_b32_e32 v174, 0
	v_mov_b32_e32 v175, 0
	v_mad_i64_i32 v[186:187], s[88:89], v185, s77, v[78:79]
	v_cmp_lt_i32_e64 s[84:85], 2, v184
	s_and_saveexec_b64 s[86:87], s[84:85]
	global_load_dwordx4 v[130:133], v[186:187], off offset:-3072
	s_or_b64 exec, exec, s[86:87]
	v_cmp_lt_i32_e64 s[84:85], 1, v184
	s_and_saveexec_b64 s[86:87], s[84:85]
	global_load_dwordx4 v[134:137], v[186:187], off offset:-1024
	s_or_b64 exec, exec, s[86:87]
	v_cmp_lt_i32_e64 s[84:85], 0, v184
	s_and_saveexec_b64 s[86:87], s[84:85]
	global_load_dwordx4 v[172:175], v[186:187], off offset:1024
	s_or_b64 exec, exec, s[86:87]
	global_load_dwordx4 v[176:179], v[186:187], off offset:3072

; __global__ void __launch_bounds__(512) mega(Params p) {
;   extern __shared__ __attribute__((aligned(16))) char lds[];
	.amdhsa_kernel _Z4mega6Params
		.amdhsa_group_segment_fixed_size 0
		.amdhsa_private_segment_fixed_size 0
		.amdhsa_kernarg_size 472
		.amdhsa_user_sgpr_count 2
		.amdhsa_user_sgpr_dispatch_ptr 0
		.amdhsa_user_sgpr_queue_ptr 0
		.amdhsa_user_sgpr_kernarg_segment_ptr 1
		.amdhsa_user_sgpr_dispatch_id 0
		.amdhsa_user_sgpr_kernarg_preload_length 0
		.amdhsa_user_sgpr_kernarg_preload_offset 0
		.amdhsa_user_sgpr_private_segment_size 0
		.amdhsa_uses_dynamic_stack 0
		.amdhsa_enable_private_segment 0
		.amdhsa_system_sgpr_workgroup_id_x 1
		.amdhsa_system_sgpr_workgroup_id_y 0
		.amdhsa_system_sgpr_workgroup_id_z 0
		.amdhsa_system_sgpr_workgroup_info 0
		.amdhsa_system_vgpr_workitem_id 2
		.amdhsa_next_free_vgpr 251
		.amdhsa_next_free_sgpr 102
		.amdhsa_accum_offset 252
		.amdhsa_reserve_vcc 1
		.amdhsa_float_round_mode_32 0
		.amdhsa_float_round_mode_16_64 0
		.amdhsa_float_denorm_mode_32 3
		.amdhsa_float_denorm_mode_16_64 3
		.amdhsa_dx10_clamp 1
		.amdhsa_ieee_mode 1
		.amdhsa_fp16_overflow 0
		.amdhsa_tg_split 0
		.amdhsa_exception_fp_ieee_invalid_op 0
		.amdhsa_exception_fp_denorm_src 0
		.amdhsa_exception_fp_ieee_div_zero 0
		.amdhsa_exception_fp_ieee_overflow 0
		.amdhsa_exception_fp_ieee_underflow 0
		.amdhsa_exception_fp_ieee_inexact 0
		.amdhsa_exception_int_div_zero 0
	.end_amdhsa_kernel

; __global__ void __launch_bounds__(512) mega(Params p) {
amdhsa.kernels:
  - .agpr_count:     0
    .args:
      - .offset:         0
        .size:           216
        .value_kind:     by_value
      - .offset:         216
        .size:           4
        .value_kind:     hidden_block_count_x
      - .offset:         220
        .size:           4
        .value_kind:     hidden_block_count_y
      - .offset:         224
        .size:           4
        .value_kind:     hidden_block_count_z
      - .offset:         228
        .size:           2
        .value_kind:     hidden_group_size_x
      - .offset:         230
        .size:           2
        .value_kind:     hidden_group_size_y
      - .offset:         232
        .size:           2
        .value_kind:     hidden_group_size_z
      - .offset:         234
        .size:           2
        .value_kind:     hidden_remainder_x
      - .offset:         236
        .size:           2
        .value_kind:     hidden_remainder_y
      - .offset:         238
        .size:           2
        .value_kind:     hidden_remainder_z
      - .offset:         256
        .size:           8
        .value_kind:     hidden_global_offset_x
      - .offset:         264
        .size:           8
        .value_kind:     hidden_global_offset_y
      - .offset:         272
        .size:           8
        .value_kind:     hidden_global_offset_z
      - .offset:         280
        .size:           2
        .value_kind:     hidden_grid_dims
      - .offset:         304
        .size:           8
        .value_kind:     hidden_multigrid_sync_arg
      - .offset:         336
        .size:           4
        .value_kind:     hidden_dynamic_lds_size
    .group_segment_fixed_size: 0
    .kernarg_segment_align: 8
    .kernarg_segment_size: 472
    .language:       OpenCL C
    .language_version:
      - 2
      - 0
    .max_flat_workgroup_size: 512
    .name:           _Z4mega6Params
    .private_segment_fixed_size: 0
    .sgpr_count:     108
    .sgpr_spill_count: 60
    .symbol:         _Z4mega6Params.kd
    .uniform_work_group_size: 1
    .uses_dynamic_stack: false
    .vgpr_count:     251
    .vgpr_spill_count: 0
    .wavefront_size: 64
